# grid barrier: non-leader workgroups issue buffer_inv sc1 on arrival (before polling), leader path unchanged
# speedup vs baseline: 1.0101x; 1.0083x over previous
; #define AF_WAIT_BAR(N) asm volatile("s_waitcnt vmcnt(" #N ") lgkmcnt(0)\n\ts_barrier" ::: "memory")
; #define AF_ROT() do { s_prev = s_cur; s_cur = s_next; s_next = (s_next == 2) ? 0 : s_next + 1; } while (0)
; #define AF_WAIT_BAR(N) asm volatile("s_waitcnt vmcnt(" #N ") lgkmcnt(0)\n\ts_barrier" ::: "memory")
; #define AF_ROT() do { s_prev = s_cur; s_cur = s_next; s_next = (s_next == 2) ? 0 : s_next + 1; } while (0)
; __device__ __forceinline__ void dense_unit(int b, int h, int qb, const bf16* Q, const bf16* __restrict__ KV, const char* __restrict__ K6N, const char* __restrict__ K6R, bf16* O, char* shm, const int tid) {
;     ...
;   int t = 1;
;   for (; t + 3 < NT; t += 2) {
;     AF_STEP(pB0, pB1, pA0, pA1, t, true, true, true);     AF_WAIT_BAR(2); AF_ROT();
.LBB0_65:
	v_lshl_add_u32 v145, s52, 13, v157
	ds_read_b64_tr_b16 v[98:99], v145 offset:15360
	ds_read_b64_tr_b16 v[100:101], v145 offset:15872
	v_add_f32_e32 v208, v50, v51
	ds_read_b64_tr_b16 v[102:103], v145 offset:19456
	ds_read_b64_tr_b16 v[104:105], v145 offset:19968
	v_add_f32_e32 v209, v52, v53
	v_add_f32_e32 v208, v54, v208
	v_add_f32_e32 v209, v55, v209
	v_add_f32_e32 v208, v56, v208
	v_add_f32_e32 v209, v57, v209
	v_add_f32_e32 v208, v58, v208
	v_cvt_pk_bf16_f32 v106, v50, v51
	v_cvt_pk_bf16_f32 v107, v52, v53
	v_cvt_pk_bf16_f32 v108, v54, v55
	v_cvt_pk_bf16_f32 v109, v56, v57
	v_mfma_scale_f32_32x32x64_f8f6f4 v[82:97], v[72:77], v[120:125], 0, v139, v0 op_sel_hi:[0,0,0] cbsz:2 blgp:2
	ds_read_b64_tr_b16 v[54:55], v145 offset:16384
	ds_read_b64_tr_b16 v[56:57], v145 offset:16896
	ds_read_b64_tr_b16 v[110:111], v145 offset:20480
	ds_read_b64_tr_b16 v[112:113], v145 offset:20992
	v_add_f32_e32 v209, v59, v209
	v_mfma_scale_f32_32x32x64_f8f6f4 v[66:81], v[66:71], v[120:125], 0, v139, v0 op_sel_hi:[0,0,0] cbsz:2 blgp:2
	v_add_f32_e32 v208, v60, v208
	v_add_f32_e32 v209, v61, v209
	v_add_f32_e32 v208, v62, v208
	v_add_f32_e32 v209, v63, v209
	v_add_f32_e32 v208, v64, v208
	v_add_f32_e32 v209, v65, v209
	v_add_f32_e32 v208, v34, v208
	v_cvt_pk_bf16_f32 v58, v58, v59
	v_cvt_pk_bf16_f32 v59, v60, v61
	v_cvt_pk_bf16_f32 v60, v62, v63
	v_cvt_pk_bf16_f32 v61, v64, v65
	ds_read_b64_tr_b16 v[62:63], v145 offset:17408
	ds_read_b64_tr_b16 v[64:65], v145 offset:17920
	ds_read_b64_tr_b16 v[50:51], v145 offset:21504
	ds_read_b64_tr_b16 v[52:53], v145 offset:22016
	v_mfma_scale_f32_32x32x64_f8f6f4 v[82:97], v[132:137], v[114:119], v[82:97], v139, v0 op_sel_hi:[0,0,0] cbsz:2 blgp:2
	v_add_f32_e32 v209, v35, v209
	v_add_f32_e32 v208, v36, v208
	v_add_f32_e32 v209, v37, v209
	v_add_f32_e32 v208, v38, v208
	v_add_f32_e32 v209, v39, v209
	v_add_f32_e32 v208, v40, v208
	v_add_f32_e32 v209, v41, v209
	v_add_f32_e32 v208, v42, v208
	v_cvt_pk_bf16_f32 v132, v34, v35
	v_cvt_pk_bf16_f32 v133, v36, v37
	v_cvt_pk_bf16_f32 v134, v38, v39
	v_cvt_pk_bf16_f32 v135, v40, v41
	s_mul_i32 s13, s62, 0x1400
	s_add_i32 m0, s13, s59
	ds_read_b64_tr_b16 v[164:165], v145 offset:18432
	ds_read_b64_tr_b16 v[166:167], v145 offset:18944
	global_load_lds_dwordx4 v151, s[22:23]
	ds_read_b64_tr_b16 v[174:175], v145 offset:22528
	ds_read_b64_tr_b16 v[176:177], v145 offset:23040
	s_add_u32 s22, s22, s56
	s_addc_u32 s23, s23, 0
	s_waitcnt lgkmcnt(14)
	v_mfma_scale_f32_32x32x64_f8f6f4 v[66:81], v[126:131], v[114:119], v[66:81], v139, v0 op_sel_hi:[0,0,0] cbsz:2 blgp:2
	v_add_f32_e32 v209, v43, v209
	v_add_f32_e32 v208, v44, v208
	v_add_f32_e32 v209, v45, v209
	v_add_f32_e32 v208, v46, v208
	v_add_f32_e32 v209, v47, v209
	v_add_f32_e32 v208, v48, v208
	v_add_f32_e32 v209, v49, v209
	v_add_f32_e32 v143, v143, v208
	v_cvt_pk_bf16_f32 v126, v42, v43
	v_cvt_pk_bf16_f32 v127, v44, v45
	v_cvt_pk_bf16_f32 v128, v46, v47
	v_cvt_pk_bf16_f32 v129, v48, v49
	s_lshl_b32 s13, s11, 13
	s_add_i32 m0, s13, s60
	v_add_f32_e32 v143, v143, v209
	global_load_lds_dwordx4 v141, s[8:9]
	s_add_u32 s8, s8, 0x40000
	s_addc_u32 s9, s9, 0
	v_mfma_f32_32x32x16_bf16 v[2:17], v[106:109], v[98:101], v[2:17]
	v_exp_f32_e32 v82, v82
	v_exp_f32_e32 v83, v83
	v_exp_f32_e32 v84, v84
	v_exp_f32_e32 v85, v85
	s_mul_i32 s52, s11, 0x1400
	v_add_u32_e32 v46, s52, v154
	v_add_u32_e32 v47, s52, v155
	ds_read_b128 v[34:37], v46
	ds_read_b64 v[38:39], v47 offset:2048
	s_waitcnt lgkmcnt(14)
	v_mfma_f32_32x32x16_bf16 v[18:33], v[106:109], v[102:105], v[18:33]
	v_exp_f32_e32 v86, v86
	v_exp_f32_e32 v87, v87
	v_exp_f32_e32 v88, v88
	v_exp_f32_e32 v89, v89
	ds_read_b128 v[40:43], v46 offset:512
	ds_read_b64 v[44:45], v47 offset:2304
	s_waitcnt lgkmcnt(14)
	v_mfma_f32_32x32x16_bf16 v[2:17], v[58:61], v[54:57], v[2:17]
	v_exp_f32_e32 v90, v90
	v_exp_f32_e32 v91, v91
	v_exp_f32_e32 v92, v92
	v_exp_f32_e32 v93, v93
	ds_read_b128 v[102:105], v46 offset:3072
	ds_read_b64 v[106:107], v47 offset:4096
	s_waitcnt lgkmcnt(14)
	v_mfma_f32_32x32x16_bf16 v[18:33], v[58:61], v[110:113], v[18:33]
	v_exp_f32_e32 v94, v94
	v_exp_f32_e32 v95, v95
	v_exp_f32_e32 v96, v96
	v_exp_f32_e32 v97, v97
	ds_read_b128 v[108:111], v46 offset:3584
	ds_read_b64 v[112:113], v47 offset:4352
	s_waitcnt lgkmcnt(14)
	v_mfma_f32_32x32x16_bf16 v[2:17], v[132:135], v[62:65], v[2:17]
	v_exp_f32_e32 v66, v66
	v_exp_f32_e32 v67, v67
	v_exp_f32_e32 v68, v68
	v_exp_f32_e32 v69, v69
	s_waitcnt lgkmcnt(12)
	v_mfma_f32_32x32x16_bf16 v[18:33], v[132:135], v[50:53], v[18:33]
	v_exp_f32_e32 v70, v70
	v_exp_f32_e32 v71, v71
	v_exp_f32_e32 v72, v72
	v_exp_f32_e32 v73, v73
	s_waitcnt lgkmcnt(10)
	v_mfma_f32_32x32x16_bf16 v[2:17], v[126:129], v[164:167], v[2:17]
	v_exp_f32_e32 v74, v74
	v_exp_f32_e32 v75, v75
	v_exp_f32_e32 v76, v76
	v_exp_f32_e32 v77, v77
	s_waitcnt lgkmcnt(8)
	v_mfma_f32_32x32x16_bf16 v[18:33], v[126:129], v[174:177], v[18:33]
	v_exp_f32_e32 v78, v78
	v_exp_f32_e32 v79, v79
	v_exp_f32_e32 v80, v80
	v_exp_f32_e32 v81, v81
	s_waitcnt vmcnt(2) lgkmcnt(0)
	s_barrier
; #define AF_WAIT_BAR(N) asm volatile("s_waitcnt vmcnt(" #N ") lgkmcnt(0)\n\ts_barrier" ::: "memory")
; #define AF_ROT() do { s_prev = s_cur; s_cur = s_next; s_next = (s_next == 2) ? 0 : s_next + 1; } while (0)
; #define AF_WAIT_BAR(N) asm volatile("s_waitcnt vmcnt(" #N ") lgkmcnt(0)\n\ts_barrier" ::: "memory")
; #define AF_ROT() do { s_prev = s_cur; s_cur = s_next; s_next = (s_next == 2) ? 0 : s_next + 1; } while (0)
; __device__ __forceinline__ void dense_unit(int b, int h, int qb, const bf16* Q, const bf16* __restrict__ KV, const char* __restrict__ K6N, const char* __restrict__ K6R, bf16* O, char* shm, const int tid) {
;     ...
;   int t = 1;
;   for (; t + 3 < NT; t += 2) {
;     AF_STEP(pB0, pB1, pA0, pA1, t, true, true, true);     AF_WAIT_BAR(2); AF_ROT();
;     AF_STEP(pA0, pA1, pB0, pB1, t + 1, true, true, true); AF_WAIT_BAR(2); AF_ROT();
;   }
	s_add_i32 s13, s11, 1
	s_cmp_lg_u32 s11, 2
	s_cselect_b32 s13, s13, 0
	v_lshl_add_u32 v145, s62, 13, v157
	ds_read_b64_tr_b16 v[126:127], v145 offset:15360
	ds_read_b64_tr_b16 v[128:129], v145 offset:15872
	v_add_f32_e32 v208, v82, v83
	ds_read_b64_tr_b16 v[130:131], v145 offset:19456
	ds_read_b64_tr_b16 v[132:133], v145 offset:19968
	v_mfma_scale_f32_32x32x64_f8f6f4 v[50:65], v[34:39], v[120:125], 0, v139, v0 op_sel_hi:[0,0,0] cbsz:2 blgp:2
	v_add_f32_e32 v209, v84, v85
	v_add_f32_e32 v208, v86, v208
	v_add_f32_e32 v209, v87, v209
	v_add_f32_e32 v208, v88, v208
	v_add_f32_e32 v209, v89, v209
	v_add_f32_e32 v208, v90, v208
	v_cvt_pk_bf16_f32 v134, v82, v83
	v_cvt_pk_bf16_f32 v135, v84, v85
	v_cvt_pk_bf16_f32 v136, v86, v87
	v_cvt_pk_bf16_f32 v137, v88, v89
	ds_read_b64_tr_b16 v[164:165], v145 offset:16384
	ds_read_b64_tr_b16 v[166:167], v145 offset:16896
	ds_read_b64_tr_b16 v[98:99], v145 offset:20480
	ds_read_b64_tr_b16 v[100:101], v145 offset:20992
	v_add_f32_e32 v209, v91, v209
	v_add_f32_e32 v208, v92, v208
	v_add_f32_e32 v209, v93, v209
	v_add_f32_e32 v208, v94, v208
	v_add_f32_e32 v209, v95, v209
	v_add_f32_e32 v208, v96, v208
	v_mfma_scale_f32_32x32x64_f8f6f4 v[34:49], v[40:45], v[120:125], 0, v139, v0 op_sel_hi:[0,0,0] cbsz:2 blgp:2
	v_add_f32_e32 v209, v97, v209
	v_add_f32_e32 v208, v66, v208
	v_cvt_pk_bf16_f32 v174, v90, v91
	v_cvt_pk_bf16_f32 v175, v92, v93
	v_cvt_pk_bf16_f32 v176, v94, v95
	v_cvt_pk_bf16_f32 v177, v96, v97
	ds_read_b64_tr_b16 v[90:91], v145 offset:17408
	ds_read_b64_tr_b16 v[92:93], v145 offset:17920
	ds_read_b64_tr_b16 v[82:83], v145 offset:21504
	ds_read_b64_tr_b16 v[84:85], v145 offset:22016
	v_mfma_scale_f32_32x32x64_f8f6f4 v[50:65], v[102:107], v[114:119], v[50:65], v139, v0 op_sel_hi:[0,0,0] cbsz:2 blgp:2
	v_add_f32_e32 v209, v67, v209
	v_add_f32_e32 v208, v68, v208
	v_add_f32_e32 v209, v69, v209
	v_add_f32_e32 v208, v70, v208
	v_add_f32_e32 v209, v71, v209
	v_add_f32_e32 v208, v72, v208
	v_add_f32_e32 v209, v73, v209
	v_add_f32_e32 v208, v74, v208
	v_cvt_pk_bf16_f32 v94, v66, v67
	v_cvt_pk_bf16_f32 v95, v68, v69
	v_cvt_pk_bf16_f32 v96, v70, v71
	v_cvt_pk_bf16_f32 v97, v72, v73
	s_add_i32 m0, s52, s59
	ds_read_b64_tr_b16 v[102:103], v145 offset:18432
	ds_read_b64_tr_b16 v[104:105], v145 offset:18944
	global_load_lds_dwordx4 v151, s[22:23]
	ds_read_b64_tr_b16 v[86:87], v145 offset:22528
	ds_read_b64_tr_b16 v[88:89], v145 offset:23040
	s_add_u32 s22, s22, s56
	s_addc_u32 s23, s23, 0
	s_waitcnt lgkmcnt(14)
	v_mfma_scale_f32_32x32x64_f8f6f4 v[34:49], v[108:113], v[114:119], v[34:49], v139, v0 op_sel_hi:[0,0,0] cbsz:2 blgp:2
	v_add_f32_e32 v209, v75, v209
	v_add_f32_e32 v208, v76, v208
	v_add_f32_e32 v209, v77, v209
	v_add_f32_e32 v208, v78, v208
	v_add_f32_e32 v209, v79, v209
	v_add_f32_e32 v208, v80, v208
	v_add_f32_e32 v209, v81, v209
	v_add_f32_e32 v143, v143, v208
	v_cvt_pk_bf16_f32 v106, v74, v75
	v_cvt_pk_bf16_f32 v107, v76, v77
	v_cvt_pk_bf16_f32 v108, v78, v79
	v_cvt_pk_bf16_f32 v109, v80, v81
	s_lshl_b32 s62, s13, 13
	s_add_i32 m0, s62, s60
	v_add_f32_e32 v143, v143, v209
	global_load_lds_dwordx4 v141, s[8:9]
	s_add_u32 s8, s8, 0x40000
	s_addc_u32 s9, s9, 0
	v_mfma_f32_32x32x16_bf16 v[2:17], v[134:137], v[126:129], v[2:17]
	v_exp_f32_e32 v50, v50
	v_exp_f32_e32 v51, v51
	v_exp_f32_e32 v52, v52
	v_exp_f32_e32 v53, v53
	s_mul_i32 s52, s13, 0x1400
	v_add_u32_e32 v78, s52, v154
	v_add_u32_e32 v79, s52, v155
	ds_read_b128 v[72:75], v78
	ds_read_b64 v[76:77], v79 offset:2048
	s_waitcnt lgkmcnt(14)
	v_mfma_f32_32x32x16_bf16 v[18:33], v[134:137], v[130:133], v[18:33]
	v_exp_f32_e32 v54, v54
	v_exp_f32_e32 v55, v55
	v_exp_f32_e32 v56, v56
	v_exp_f32_e32 v57, v57
	ds_read_b128 v[66:69], v78 offset:512
	ds_read_b64 v[70:71], v79 offset:2304
	s_waitcnt lgkmcnt(14)
	v_mfma_f32_32x32x16_bf16 v[2:17], v[174:177], v[164:167], v[2:17]
	v_exp_f32_e32 v58, v58
	v_exp_f32_e32 v59, v59
	v_exp_f32_e32 v60, v60
	v_exp_f32_e32 v61, v61
	ds_read_b128 v[132:135], v78 offset:3072
	ds_read_b64 v[136:137], v79 offset:4096
	s_waitcnt lgkmcnt(14)
	v_mfma_f32_32x32x16_bf16 v[18:33], v[174:177], v[98:101], v[18:33]
	v_exp_f32_e32 v62, v62
	v_exp_f32_e32 v63, v63
	v_exp_f32_e32 v64, v64
	v_exp_f32_e32 v65, v65
	ds_read_b128 v[126:129], v78 offset:3584
	ds_read_b64 v[130:131], v79 offset:4352
	s_waitcnt lgkmcnt(14)
	v_mfma_f32_32x32x16_bf16 v[2:17], v[94:97], v[90:93], v[2:17]
	v_exp_f32_e32 v34, v34
	v_exp_f32_e32 v35, v35
	v_exp_f32_e32 v36, v36
	v_exp_f32_e32 v37, v37
	s_waitcnt lgkmcnt(12)
	v_mfma_f32_32x32x16_bf16 v[18:33], v[94:97], v[82:85], v[18:33]
	v_exp_f32_e32 v38, v38
	v_exp_f32_e32 v39, v39
	v_exp_f32_e32 v40, v40
	v_exp_f32_e32 v41, v41
	s_waitcnt lgkmcnt(10)
	v_mfma_f32_32x32x16_bf16 v[2:17], v[106:109], v[102:105], v[2:17]
	v_exp_f32_e32 v42, v42
	v_exp_f32_e32 v43, v43
	v_exp_f32_e32 v44, v44
	v_exp_f32_e32 v45, v45
	s_waitcnt lgkmcnt(8)
	v_mfma_f32_32x32x16_bf16 v[18:33], v[106:109], v[86:89], v[18:33]
	v_exp_f32_e32 v46, v46
	v_exp_f32_e32 v47, v47
	v_exp_f32_e32 v48, v48
	v_exp_f32_e32 v49, v49
	s_add_i32 s53, s13, 1
	s_cmp_lg_u32 s13, 2
	s_mov_b32 s52, s11
	s_cselect_b32 s11, s53, 0
	s_add_i32 s61, s61, 2
	s_waitcnt vmcnt(2) lgkmcnt(0)
	s_barrier
	s_addk_i32 s7, 0x80
	s_mov_b32 s62, s13
	s_cmpk_lt_u32 s61, 0x7f
	s_cbranch_scc1 .LBB0_65
; #define AF_WAIT_BAR(N) asm volatile("s_waitcnt vmcnt(" #N ") lgkmcnt(0)\n\ts_barrier" ::: "memory")
; #define AF_ROT() do { s_prev = s_cur; s_cur = s_next; s_next = (s_next == 2) ? 0 : s_next + 1; } while (0)
; #define AF_WAIT_BAR(N) asm volatile("s_waitcnt vmcnt(" #N ") lgkmcnt(0)\n\ts_barrier" ::: "memory")
; #define AF_ROT() do { s_prev = s_cur; s_cur = s_next; s_next = (s_next == 2) ? 0 : s_next + 1; } while (0)
; __device__ __forceinline__ void dense_unit(int b, int h, int qb, const bf16* Q, const bf16* __restrict__ KV, const char* __restrict__ K6N, const char* __restrict__ K6R, bf16* O, char* shm, const int tid) {
;     ...
;   AF_STEP(pB0, pB1, pA0, pA1, NT - 3, false, true, true);  AF_WAIT_BAR(1); AF_ROT();
	s_nop 0
	s_nop 0
	s_nop 0
	s_nop 0
	s_nop 0
	s_nop 0
	s_nop 0
	s_nop 0
	s_nop 0
	s_nop 0
	s_nop 0
	s_nop 0
	s_nop 0
	s_nop 0
	s_nop 0
	s_nop 0
	s_nop 0
	s_nop 0
	s_nop 0
	s_nop 0
	s_nop 0
	s_nop 0
	s_nop 0
	s_nop 0
	s_nop 0
	s_nop 0
	s_nop 0
	s_nop 0
	s_and_b32 s7, s55, 0x3fffffc0
	s_lshl_b32 s7, s7, 2
	s_add_i32 s8, s7, 0
	ds_read_b64_tr_b16 v[82:83], v157 offset:31744
	ds_read_b64_tr_b16 v[84:85], v157 offset:32256
	v_add_f32_e32 v78, v50, v51
	ds_read_b64_tr_b16 v[86:87], v157 offset:35840
	ds_read_b64_tr_b16 v[88:89], v157 offset:36352
	v_add_f32_e32 v78, v52, v78
	v_add_f32_e32 v78, v53, v78
	v_add_f32_e32 v78, v54, v78
	v_add_f32_e32 v78, v55, v78
	v_add_f32_e32 v78, v56, v78
	v_add_f32_e32 v78, v57, v78
	v_cvt_pk_bf16_f32 v50, v50, v51
	v_cvt_pk_bf16_f32 v51, v52, v53
	v_cvt_pk_bf16_f32 v52, v54, v55
	v_cvt_pk_bf16_f32 v53, v56, v57
	s_waitcnt lgkmcnt(10)
	v_mfma_scale_f32_32x32x64_f8f6f4 v[98:113], v[72:77], v[120:125], 0, v139, v0 op_sel_hi:[0,0,0] cbsz:2 blgp:2
	ds_read_b64_tr_b16 v[54:55], v157 offset:32768
	ds_read_b64_tr_b16 v[56:57], v157 offset:33280
	ds_read_b64_tr_b16 v[90:91], v157 offset:36864
	ds_read_b64_tr_b16 v[92:93], v157 offset:37376
	v_add_f32_e32 v72, v58, v78
	v_add_f32_e32 v72, v59, v72
	v_add_f32_e32 v72, v60, v72
	v_add_f32_e32 v72, v61, v72
	v_add_f32_e32 v72, v62, v72
	v_add_f32_e32 v94, v63, v72
	v_add_f32_e32 v94, v64, v94
	v_add_f32_e32 v145, v65, v94
	v_cvt_pk_bf16_f32 v58, v58, v59
	v_cvt_pk_bf16_f32 v59, v60, v61
	v_cvt_pk_bf16_f32 v60, v62, v63
	v_cvt_pk_bf16_f32 v61, v64, v65
	s_waitcnt lgkmcnt(12)
	v_mfma_scale_f32_32x32x64_f8f6f4 v[66:81], v[66:71], v[120:125], 0, v139, v0 op_sel_hi:[0,0,0] cbsz:2 blgp:2
	ds_read_b64_tr_b16 v[62:63], v157 offset:33792
	ds_read_b64_tr_b16 v[64:65], v157 offset:34304
	ds_read_b64_tr_b16 v[94:95], v157 offset:37888
	ds_read_b64_tr_b16 v[96:97], v157 offset:38400
	s_waitcnt lgkmcnt(14)
	v_mfma_scale_f32_32x32x64_f8f6f4 v[98:113], v[132:137], v[114:119], v[98:113], v139, v0 op_sel_hi:[0,0,0] cbsz:2 blgp:2
	v_add_f32_e32 v132, v34, v145
	v_add_f32_e32 v132, v35, v132
	v_add_f32_e32 v132, v36, v132
	v_add_f32_e32 v132, v37, v132
	v_add_f32_e32 v132, v38, v132
	v_add_f32_e32 v132, v39, v132
	v_add_f32_e32 v132, v40, v132
	v_add_f32_e32 v132, v41, v132
	v_cvt_pk_bf16_f32 v134, v34, v35
	v_cvt_pk_bf16_f32 v135, v36, v37
	v_cvt_pk_bf16_f32 v136, v38, v39
	v_cvt_pk_bf16_f32 v137, v40, v41
	ds_read_b64_tr_b16 v[174:175], v157 offset:34816
	ds_read_b64_tr_b16 v[176:177], v157 offset:35328
	ds_read_b64_tr_b16 v[178:179], v157 offset:38912
	ds_read_b64_tr_b16 v[180:181], v157 offset:39424
	v_add_f32_e32 v34, v42, v132
	v_add_f32_e32 v34, v43, v34
	v_add_f32_e32 v34, v44, v34
	v_add_f32_e32 v34, v45, v34
	v_add_f32_e32 v34, v46, v34
	v_add_f32_e32 v34, v47, v34
	v_add_f32_e32 v34, v48, v34
	s_waitcnt lgkmcnt(14)
	v_mfma_scale_f32_32x32x64_f8f6f4 v[66:81], v[126:131], v[114:119], v[66:81], v139, v0 op_sel_hi:[0,0,0] cbsz:2 blgp:2
	v_add_f32_e32 v126, v49, v34
	v_cvt_pk_bf16_f32 v182, v42, v43
	v_cvt_pk_bf16_f32 v183, v44, v45
	v_cvt_pk_bf16_f32 v184, v46, v47
	v_cvt_pk_bf16_f32 v185, v48, v49
	s_or_b32 s52, s6, 0x1f80
	s_ashr_i32 s53, s52, 31
	s_lshl_b64 s[52:53], s[52:53], 12
	s_add_u32 s52, s1, s52
	s_addc_u32 s53, s54, s53
	s_mov_b32 s7, m0
	s_mov_b32 m0, s12
	s_nop 0
	global_load_lds_dwordx4 v141, s[52:53]
	s_mov_b32 m0, s7
	v_mfma_f32_32x32x16_bf16 v[2:17], v[50:53], v[82:85], v[2:17]
	v_exp_f32_e32 v98, v98
	v_exp_f32_e32 v99, v99
	v_exp_f32_e32 v100, v100
	v_exp_f32_e32 v101, v101
	ds_read_b128 v[34:37], v154 offset:5120
	ds_read_b64 v[38:39], v155 offset:7168
	s_waitcnt lgkmcnt(14)
	v_mfma_f32_32x32x16_bf16 v[18:33], v[50:53], v[86:89], v[18:33]
	v_exp_f32_e32 v102, v102
	v_exp_f32_e32 v103, v103
	v_exp_f32_e32 v104, v104
	v_exp_f32_e32 v105, v105
	ds_read_b128 v[40:43], v154 offset:5632
	ds_read_b64 v[44:45], v155 offset:7424
	s_waitcnt lgkmcnt(14)
	v_mfma_f32_32x32x16_bf16 v[2:17], v[58:61], v[54:57], v[2:17]
	v_exp_f32_e32 v106, v106
	v_exp_f32_e32 v107, v107
	v_exp_f32_e32 v108, v108
	v_exp_f32_e32 v109, v109
	ds_read_b128 v[128:131], v154 offset:8192
	ds_read_b64 v[132:133], v155 offset:9216
	s_waitcnt lgkmcnt(14)
	v_mfma_f32_32x32x16_bf16 v[18:33], v[58:61], v[90:93], v[18:33]
	v_exp_f32_e32 v110, v110
	v_exp_f32_e32 v111, v111
	v_exp_f32_e32 v112, v112
	v_exp_f32_e32 v113, v113
	ds_read_b128 v[164:167], v154 offset:8704
	ds_read_b64 v[168:169], v155 offset:9472
	s_waitcnt lgkmcnt(14)
	v_mfma_f32_32x32x16_bf16 v[2:17], v[134:137], v[62:65], v[2:17]
	v_exp_f32_e32 v66, v66
	v_exp_f32_e32 v67, v67
	v_exp_f32_e32 v68, v68
	v_exp_f32_e32 v69, v69
	s_waitcnt lgkmcnt(12)
	v_mfma_f32_32x32x16_bf16 v[18:33], v[134:137], v[94:97], v[18:33]
	v_exp_f32_e32 v70, v70
	v_exp_f32_e32 v71, v71
	v_exp_f32_e32 v72, v72
	v_exp_f32_e32 v73, v73
	s_waitcnt lgkmcnt(10)
	v_mfma_f32_32x32x16_bf16 v[2:17], v[182:185], v[174:177], v[2:17]
	v_exp_f32_e32 v74, v74
	v_exp_f32_e32 v75, v75
	v_exp_f32_e32 v76, v76
	v_exp_f32_e32 v77, v77
	s_waitcnt lgkmcnt(8)
	v_mfma_f32_32x32x16_bf16 v[18:33], v[182:185], v[178:181], v[18:33]
	v_exp_f32_e32 v78, v78
	v_exp_f32_e32 v79, v79
	v_exp_f32_e32 v80, v80
	v_exp_f32_e32 v81, v81
	s_waitcnt vmcnt(1) lgkmcnt(0)
	s_barrier
; #define AF_WAIT_BAR(N) asm volatile("s_waitcnt vmcnt(" #N ") lgkmcnt(0)\n\ts_barrier" ::: "memory")
; #define AF_ROT() do { s_prev = s_cur; s_cur = s_next; s_next = (s_next == 2) ? 0 : s_next + 1; } while (0)
; #define AF_WAIT_BAR(N) asm volatile("s_waitcnt vmcnt(" #N ") lgkmcnt(0)\n\ts_barrier" ::: "memory")
; #define AF_ROT() do { s_prev = s_cur; s_cur = s_next; s_next = (s_next == 2) ? 0 : s_next + 1; } while (0)
; __device__ __forceinline__ void dense_unit(int b, int h, int qb, const bf16* Q, const bf16* __restrict__ KV, const char* __restrict__ K6N, const char* __restrict__ K6R, bf16* O, char* shm, const int tid) {
;     ...
;   AF_STEP(pA0, pA1, pB0, pB1, NT - 2, false, true, true);  AF_WAIT_BAR(0); AF_ROT();
	ds_read_b64_tr_b16 v[46:47], v157 offset:15360
	ds_read_b64_tr_b16 v[48:49], v157 offset:15872
	v_add_f32_e32 v50, v98, v99
	ds_read_b64_tr_b16 v[134:135], v157 offset:19456
	ds_read_b64_tr_b16 v[136:137], v157 offset:19968
	v_add_f32_e32 v50, v100, v50
	v_add_f32_e32 v50, v101, v50
	v_add_f32_e32 v50, v102, v50
	v_add_f32_e32 v50, v103, v50
	v_add_f32_e32 v50, v104, v50
	v_add_f32_e32 v50, v105, v50
	v_cvt_pk_bf16_f32 v174, v98, v99
	v_cvt_pk_bf16_f32 v175, v100, v101
	v_cvt_pk_bf16_f32 v176, v102, v103
	v_cvt_pk_bf16_f32 v177, v104, v105
	s_waitcnt lgkmcnt(10)
	v_mfma_scale_f32_32x32x64_f8f6f4 v[82:97], v[34:39], v[120:125], 0, v139, v0 op_sel_hi:[0,0,0] cbsz:2 blgp:2
	ds_read_b64_tr_b16 v[100:101], v157 offset:16384
	ds_read_b64_tr_b16 v[102:103], v157 offset:16896
	ds_read_b64_tr_b16 v[178:179], v157 offset:20480
	ds_read_b64_tr_b16 v[180:181], v157 offset:20992
	v_add_f32_e32 v34, v106, v50
	v_add_f32_e32 v34, v107, v34
	v_add_f32_e32 v34, v108, v34
	v_add_f32_e32 v34, v109, v34
	v_add_f32_e32 v34, v110, v34
	v_add_f32_e32 v34, v111, v34
	v_add_f32_e32 v34, v112, v34
	v_add_f32_e32 v34, v113, v34
	v_cvt_pk_bf16_f32 v106, v106, v107
	v_cvt_pk_bf16_f32 v107, v108, v109
	v_cvt_pk_bf16_f32 v108, v110, v111
	v_cvt_pk_bf16_f32 v109, v112, v113
	s_waitcnt lgkmcnt(12)
	v_mfma_scale_f32_32x32x64_f8f6f4 v[50:65], v[40:45], v[120:125], 0, v139, v0 op_sel_hi:[0,0,0] cbsz:2 blgp:2
	ds_read_b64_tr_b16 v[182:183], v157 offset:17408
	ds_read_b64_tr_b16 v[184:185], v157 offset:17920
	ds_read_b64_tr_b16 v[204:205], v157 offset:21504
	ds_read_b64_tr_b16 v[206:207], v157 offset:22016
	v_add_f32_e32 v34, v66, v34
	v_add_f32_e32 v34, v67, v34
	v_add_f32_e32 v34, v68, v34
	v_add_f32_e32 v34, v69, v34
	v_add_f32_e32 v34, v70, v34
	v_add_f32_e32 v34, v71, v34
	v_add_f32_e32 v34, v72, v34
	v_add_f32_e32 v34, v73, v34
	v_cvt_pk_bf16_f32 v66, v66, v67
	v_cvt_pk_bf16_f32 v67, v68, v69
	v_cvt_pk_bf16_f32 v68, v70, v71
	v_cvt_pk_bf16_f32 v69, v72, v73
	s_waitcnt lgkmcnt(14)
	v_mfma_scale_f32_32x32x64_f8f6f4 v[82:97], v[128:133], v[114:119], v[82:97], v139, v0 op_sel_hi:[0,0,0] cbsz:2 blgp:2
	ds_read_b64_tr_b16 v[70:71], v157 offset:18432
	ds_read_b64_tr_b16 v[72:73], v157 offset:18944
	ds_read_b64_tr_b16 v[128:129], v157 offset:22528
	ds_read_b64_tr_b16 v[130:131], v157 offset:23040
	v_add_f32_e32 v34, v74, v34
	v_add_f32_e32 v34, v75, v34
	v_add_f32_e32 v34, v76, v34
	v_add_f32_e32 v34, v77, v34
	v_add_f32_e32 v34, v78, v34
	v_add_f32_e32 v34, v79, v34
	v_add_f32_e32 v34, v80, v34
	v_add_f32_e32 v98, v81, v34
	v_cvt_pk_bf16_f32 v74, v74, v75
	v_cvt_pk_bf16_f32 v75, v76, v77
	v_cvt_pk_bf16_f32 v76, v78, v79
	v_cvt_pk_bf16_f32 v77, v80, v81
	s_waitcnt lgkmcnt(14)
	v_mfma_scale_f32_32x32x64_f8f6f4 v[50:65], v[164:169], v[114:119], v[50:65], v139, v0 op_sel_hi:[0,0,0] cbsz:2 blgp:2
	s_or_b32 s6, s6, 0x1fc0
	s_ashr_i32 s7, s6, 31
	s_lshl_b64 s[6:7], s[6:7], 12
	s_add_u32 s6, s1, s6
	s_addc_u32 s7, s54, s7
	s_mov_b32 s1, m0
	s_mov_b32 m0, s10
	s_nop 0
	global_load_lds_dwordx4 v141, s[6:7]
	s_mov_b32 m0, s1
	v_mfma_f32_32x32x16_bf16 v[2:17], v[174:177], v[46:49], v[2:17]
	v_exp_f32_e32 v82, v82
	v_exp_f32_e32 v83, v83
	v_exp_f32_e32 v84, v84
	v_exp_f32_e32 v85, v85
	ds_read_b128 v[34:37], v154 offset:10240
	ds_read_b64 v[38:39], v155 offset:12288
	s_waitcnt lgkmcnt(14)
	v_mfma_f32_32x32x16_bf16 v[18:33], v[174:177], v[134:137], v[18:33]
	v_exp_f32_e32 v86, v86
	v_exp_f32_e32 v87, v87
	v_exp_f32_e32 v88, v88
	v_exp_f32_e32 v89, v89
	ds_read_b128 v[40:43], v154 offset:10752
	ds_read_b64 v[44:45], v155 offset:12544
	s_waitcnt lgkmcnt(14)
	v_mfma_f32_32x32x16_bf16 v[2:17], v[106:109], v[100:103], v[2:17]
	v_exp_f32_e32 v90, v90
	v_exp_f32_e32 v91, v91
	v_exp_f32_e32 v92, v92
	v_exp_f32_e32 v93, v93
	ds_read_b128 v[100:103], v154 offset:13312
	ds_read_b64 v[104:105], v155 offset:14336
	s_waitcnt lgkmcnt(14)
	v_mfma_f32_32x32x16_bf16 v[18:33], v[106:109], v[178:181], v[18:33]
	v_exp_f32_e32 v94, v94
	v_exp_f32_e32 v95, v95
	v_exp_f32_e32 v96, v96
	v_exp_f32_e32 v97, v97
	ds_read_b128 v[106:109], v154 offset:13824
	ds_read_b64 v[110:111], v155 offset:14592
	s_waitcnt lgkmcnt(14)
	v_mfma_f32_32x32x16_bf16 v[2:17], v[66:69], v[182:185], v[2:17]
	v_exp_f32_e32 v50, v50
	v_exp_f32_e32 v51, v51
	v_exp_f32_e32 v52, v52
	v_exp_f32_e32 v53, v53
	s_waitcnt lgkmcnt(12)
	v_mfma_f32_32x32x16_bf16 v[18:33], v[66:69], v[204:207], v[18:33]
	v_exp_f32_e32 v54, v54
	v_exp_f32_e32 v55, v55
	v_exp_f32_e32 v56, v56
	v_exp_f32_e32 v57, v57
	s_waitcnt lgkmcnt(10)
	v_mfma_f32_32x32x16_bf16 v[2:17], v[74:77], v[70:73], v[2:17]
	v_exp_f32_e32 v58, v58
	v_exp_f32_e32 v59, v59
	v_exp_f32_e32 v60, v60
	v_exp_f32_e32 v61, v61
	s_waitcnt lgkmcnt(8)
	v_mfma_f32_32x32x16_bf16 v[18:33], v[74:77], v[128:131], v[18:33]
	v_exp_f32_e32 v62, v62
	v_exp_f32_e32 v63, v63
	v_exp_f32_e32 v64, v64
	v_exp_f32_e32 v65, v65
	s_waitcnt vmcnt(0) lgkmcnt(0)
	s_barrier
; #define AF_SBAR() __builtin_amdgcn_sched_barrier(0)
; __device__ __forceinline__ s16x4 vtr(lds_cptr p) { return __builtin_bit_cast(s16x4, __builtin_amdgcn_ds_read_tr16_b64_v4i16((__attribute__((address_space(3))) v4i16_t*)p)); }
; #define AF_MF(a, b, c) __builtin_amdgcn_mfma_f32_32x32x16_bf16(a, b, c, 0, 0, 0)
; #define AF_PKW(P, B) cvtpk_s(P[B], P[B + 1])
; #define AF_SBAR() __builtin_amdgcn_sched_barrier(0)
; __device__ __forceinline__ s16x4 vtr(lds_cptr p) { return __builtin_bit_cast(s16x4, __builtin_amdgcn_ds_read_tr16_b64_v4i16((__attribute__((address_space(3))) v4i16_t*)p)); }
; #define AF_PKW(P, B) cvtpk_s(P[B], P[B + 1])
; #define AF_MF(a, b, c) __builtin_amdgcn_mfma_f32_32x32x16_bf16(a, b, c, 0, 0, 0)
; __device__ __forceinline__ void dense_unit(int b, int h, int qb, const bf16* Q, const bf16* __restrict__ KV, const char* __restrict__ K6N, const char* __restrict__ K6R, bf16* O, char* shm, const int tid) {
;     ...
;   AF_STEP(pB0, pB1, pA0, pA1, NT - 1, false, false, false);
;   { float sacc = pB0[0] + pB0[1];
; #pragma unroll
;     for (int r = 2; r < 16; ++r) sacc += pB0[r];
; #pragma unroll
;     for (int r = 0; r < 16; ++r) sacc += pB1[r];
;     l_reg += sacc;
;     pw0 = (u32x4){AF_PKW(pB0, 0), AF_PKW(pB0, 2), AF_PKW(pB0, 4), AF_PKW(pB0, 6)}; pw1 = (u32x4){AF_PKW(pB0, 8), AF_PKW(pB0, 10), AF_PKW(pB0, 12), AF_PKW(pB0, 14)};
;     pw2 = (u32x4){AF_PKW(pB1, 0), AF_PKW(pB1, 2), AF_PKW(pB1, 4), AF_PKW(pB1, 6)}; pw3 = (u32x4){AF_PKW(pB1, 8), AF_PKW(pB1, 10), AF_PKW(pB1, 12), AF_PKW(pB1, 14)};
;     AF_SBAR();
;     const lds_cptr vp_ = vp0 + s_cur * VSLOT;
; #pragma unroll
;     for (int i = 0; i < 8; ++i) { vlo[i] = vtr(vp_ + ((i >> 2) * 4096 + (i & 3) * 1024)); vhi[i] = vtr(vp_ + ((i >> 2) * 4096 + (i & 3) * 1024 + 512)); }
;     o[0] = AF_MF(AF_PAF(0), AF_VFR(0), o[0]); o[1] = AF_MF(AF_PAF(0), AF_VFR(4), o[1]);
	ds_read_b64_tr_b16 v[128:129], v157 offset:23552
	ds_read_b64_tr_b16 v[130:131], v157 offset:24064
	v_add_f32_e32 v46, v82, v83
	ds_read_b64_tr_b16 v[132:133], v157 offset:27648
	ds_read_b64_tr_b16 v[134:135], v157 offset:28160
	v_add_f32_e32 v46, v84, v46
	v_add_f32_e32 v46, v85, v46
	v_add_f32_e32 v46, v86, v46
	v_add_f32_e32 v46, v87, v46
	v_add_f32_e32 v46, v88, v46
	v_add_f32_e32 v46, v89, v46
	v_cvt_pk_bf16_f32 v82, v82, v83
	v_cvt_pk_bf16_f32 v83, v84, v85
	v_cvt_pk_bf16_f32 v84, v86, v87
	v_cvt_pk_bf16_f32 v85, v88, v89
	s_waitcnt lgkmcnt(10)
	v_mfma_scale_f32_32x32x64_f8f6f4 v[66:81], v[34:39], v[120:125], 0, v139, v0 op_sel_hi:[0,0,0] cbsz:2 blgp:2
	ds_read_b64_tr_b16 v[86:87], v157 offset:24576
	ds_read_b64_tr_b16 v[88:89], v157 offset:25088
	ds_read_b64_tr_b16 v[164:165], v157 offset:28672
	ds_read_b64_tr_b16 v[166:167], v157 offset:29184
	v_add_f32_e32 v34, v90, v46
	v_add_f32_e32 v34, v91, v34
	v_add_f32_e32 v34, v92, v34
	v_add_f32_e32 v34, v93, v34
	v_add_f32_e32 v34, v94, v34
	v_add_f32_e32 v99, v95, v34
	s_waitcnt lgkmcnt(12)
	v_mfma_scale_f32_32x32x64_f8f6f4 v[34:49], v[40:45], v[120:125], 0, v139, v0 op_sel_hi:[0,0,0] cbsz:2 blgp:2
	v_add_f32_e32 v99, v96, v99
	v_add_f32_e32 v99, v97, v99
	v_cvt_pk_bf16_f32 v90, v90, v91
	v_cvt_pk_bf16_f32 v91, v92, v93
	v_cvt_pk_bf16_f32 v92, v94, v95
	v_cvt_pk_bf16_f32 v93, v96, v97
	ds_read_b64_tr_b16 v[94:95], v157 offset:25600
	ds_read_b64_tr_b16 v[96:97], v157 offset:26112
	ds_read_b64_tr_b16 v[120:121], v157 offset:29696
	ds_read_b64_tr_b16 v[122:123], v157 offset:30208
	v_add_f32_e32 v99, v50, v99
	v_add_f32_e32 v99, v51, v99
	v_add_f32_e32 v99, v52, v99
	v_add_f32_e32 v99, v53, v99
	v_add_f32_e32 v99, v54, v99
	v_add_f32_e32 v99, v55, v99
	v_add_f32_e32 v99, v56, v99
	v_add_f32_e32 v99, v57, v99
	v_cvt_pk_bf16_f32 v50, v50, v51
	v_cvt_pk_bf16_f32 v51, v52, v53
	v_cvt_pk_bf16_f32 v52, v54, v55
	v_cvt_pk_bf16_f32 v53, v56, v57
	s_waitcnt lgkmcnt(14)
	v_mfma_scale_f32_32x32x64_f8f6f4 v[66:81], v[100:105], v[114:119], v[66:81], v139, v0 op_sel_hi:[0,0,0] cbsz:2 blgp:2
	ds_read_b64_tr_b16 v[54:55], v157 offset:26624
	ds_read_b64_tr_b16 v[56:57], v157 offset:27136
	ds_read_b64_tr_b16 v[100:101], v157 offset:30720
	ds_read_b64_tr_b16 v[102:103], v157 offset:31232
	s_waitcnt lgkmcnt(14)
	v_mfma_scale_f32_32x32x64_f8f6f4 v[34:49], v[106:111], v[114:119], v[34:49], v139, v0 op_sel_hi:[0,0,0] cbsz:2 blgp:2
	v_add_f32_e32 v0, v58, v99
	v_add_f32_e32 v0, v59, v0
	v_add_f32_e32 v0, v60, v0
	v_add_f32_e32 v0, v61, v0
	v_add_f32_e32 v0, v62, v0
	v_add_f32_e32 v0, v63, v0
	v_add_f32_e32 v0, v64, v0
	v_add_f32_e32 v0, v65, v0
	v_cvt_pk_bf16_f32 v58, v58, v59
	v_cvt_pk_bf16_f32 v59, v60, v61
	v_cvt_pk_bf16_f32 v60, v62, v63
	v_cvt_pk_bf16_f32 v61, v64, v65
	v_mfma_f32_32x32x16_bf16 v[2:17], v[82:85], v[128:131], v[2:17]
	v_exp_f32_e32 v66, v66
	v_exp_f32_e32 v67, v67
	v_exp_f32_e32 v68, v68
	v_exp_f32_e32 v69, v69
	s_waitcnt lgkmcnt(12)
	v_mfma_f32_32x32x16_bf16 v[18:33], v[82:85], v[132:135], v[18:33]
	v_exp_f32_e32 v70, v70
	v_exp_f32_e32 v71, v71
	v_exp_f32_e32 v72, v72
	v_exp_f32_e32 v73, v73
	s_waitcnt lgkmcnt(10)
	v_mfma_f32_32x32x16_bf16 v[2:17], v[90:93], v[86:89], v[2:17]
	v_exp_f32_e32 v74, v74
	v_exp_f32_e32 v75, v75
	v_exp_f32_e32 v76, v76
	v_exp_f32_e32 v77, v77
	s_waitcnt lgkmcnt(8)
	v_mfma_f32_32x32x16_bf16 v[18:33], v[90:93], v[164:167], v[18:33]
	v_exp_f32_e32 v78, v78
	v_exp_f32_e32 v79, v79
	v_exp_f32_e32 v80, v80
	v_exp_f32_e32 v81, v81
	s_waitcnt lgkmcnt(6)
	v_mfma_f32_32x32x16_bf16 v[2:17], v[50:53], v[94:97], v[2:17]
	v_exp_f32_e32 v34, v34
	v_exp_f32_e32 v35, v35
	v_exp_f32_e32 v36, v36
	v_exp_f32_e32 v37, v37
	s_waitcnt lgkmcnt(4)
	v_mfma_f32_32x32x16_bf16 v[18:33], v[50:53], v[120:123], v[18:33]
	v_exp_f32_e32 v38, v38
	v_exp_f32_e32 v39, v39
	v_exp_f32_e32 v40, v40
	v_exp_f32_e32 v41, v41
	s_waitcnt lgkmcnt(2)
	v_mfma_f32_32x32x16_bf16 v[2:17], v[58:61], v[54:57], v[2:17]
	v_exp_f32_e32 v42, v42
	v_exp_f32_e32 v43, v43
	v_exp_f32_e32 v44, v44
	v_exp_f32_e32 v45, v45
	s_waitcnt lgkmcnt(0)
	v_mfma_f32_32x32x16_bf16 v[18:33], v[58:61], v[100:103], v[18:33]
	v_exp_f32_e32 v46, v46
	v_exp_f32_e32 v47, v47
	v_exp_f32_e32 v48, v48
	v_exp_f32_e32 v49, v49
	v_add_f32_e32 v50, v66, v67
	v_add_f32_e32 v50, v68, v50
	v_add_f32_e32 v50, v69, v50
	v_add_f32_e32 v50, v70, v50
	v_add_f32_e32 v50, v71, v50
	v_add_f32_e32 v50, v72, v50
	v_add_f32_e32 v50, v73, v50
	v_add_f32_e32 v50, v74, v50
	v_add_f32_e32 v50, v75, v50
	v_add_f32_e32 v50, v76, v50
	v_add_f32_e32 v50, v77, v50
	v_add_f32_e32 v50, v78, v50
	v_add_f32_e32 v50, v79, v50
	v_add_f32_e32 v50, v80, v50
	v_add_f32_e32 v82, v81, v50
	v_add_f32_e32 v50, v143, v126
	v_add_f32_e32 v50, v50, v98
	v_add_f32_e32 v0, v50, v0
	v_cvt_pk_bf16_f32 v50, v66, v67
	v_cvt_pk_bf16_f32 v51, v68, v69
	v_cvt_pk_bf16_f32 v52, v70, v71
	v_cvt_pk_bf16_f32 v53, v72, v73
	v_cvt_pk_bf16_f32 v54, v74, v75
	v_cvt_pk_bf16_f32 v55, v76, v77
	v_cvt_pk_bf16_f32 v56, v78, v79
	v_cvt_pk_bf16_f32 v57, v80, v81
	v_cvt_pk_bf16_f32 v58, v34, v35
	v_cvt_pk_bf16_f32 v59, v36, v37
	v_cvt_pk_bf16_f32 v60, v38, v39
	v_cvt_pk_bf16_f32 v61, v40, v41
	v_cvt_pk_bf16_f32 v62, v42, v43
	v_cvt_pk_bf16_f32 v63, v44, v45
	v_cvt_pk_bf16_f32 v64, v46, v47
	v_cvt_pk_bf16_f32 v65, v48, v49
	ds_read_b64_tr_b16 v[66:67], v157 offset:31744
	ds_read_b64_tr_b16 v[68:69], v157 offset:32256
	v_add_f32_e32 v34, v34, v82
	v_add_f32_e32 v34, v35, v34
	v_add_f32_e32 v34, v36, v34
	v_add_f32_e32 v34, v37, v34
	s_waitcnt lgkmcnt(0)
; __device__ __forceinline__ int crow(int r, int hi) { return (r & 3) + 8 * (r >> 2) + 4 * hi; }
;   __device__ __forceinline__ bf16* orow(int wid, int row) const { return O + (long)(8192 * b + qpos0(wid) + row) * 1024 + 64 * head(wid); }
;   __device__ __forceinline__ bf16* orow(int wid, int row) const { return O + (long)(8192 * b + 64 * qrow(wid) + 32 * (wid & 1) + row) * 1024 + 512 + 64 * h; }
; __device__ __forceinline__ int crow(int r, int hi) { return (r & 3) + 8 * (r >> 2) + 4 * hi; }
; __device__ __forceinline__ unsigned cvtpk_s(float lo, float hi) { f32x2_t v = {lo, hi}; bf16x2_t b = __builtin_convertvector(v, bf16x2_t); return __builtin_bit_cast(unsigned, b); }
; __device__ __forceinline__ void dense_unit(int b, int h, int qb, const bf16* Q, const bf16* __restrict__ KV, const char* __restrict__ K6N, const char* __restrict__ K6R, bf16* O, char* shm, const int tid) {
;     ...
;     o[0] = AF_MF(AF_PAF(0), AF_VFR(0), o[0]); o[1] = AF_MF(AF_PAF(0), AF_VFR(4), o[1]);
;     o[0] = AF_MF(AF_PAF(1), AF_VFR(1), o[0]); o[1] = AF_MF(AF_PAF(1), AF_VFR(5), o[1]);
;     o[0] = AF_MF(AF_PAF(2), AF_VFR(2), o[0]); o[1] = AF_MF(AF_PAF(2), AF_VFR(6), o[1]);
;     o[0] = AF_MF(AF_PAF(3), AF_VFR(3), o[0]); o[1] = AF_MF(AF_PAF(3), AF_VFR(7), o[1]); }
;   { auto rr = __builtin_amdgcn_permlane32_swap(__float_as_uint(l_reg), __float_as_uint(l_reg), false, false); l_reg = __uint_as_float(rr[0]) + __uint_as_float(rr[1]); }
;   if (hi == 0) wsf[32 + r32] = l_reg; asm volatile("s_waitcnt lgkmcnt(0)" ::: "memory");
;   float rli[16];
; #pragma unroll
;   for (int r = 0; r < 16; ++r) rli[r] = __builtin_amdgcn_rcpf(wsf[32 + crow(r, hi)]);
;   bf16* Ow = O + (long)(8192 * b + 256 * qb + 32 * wid) * 1024 + 64 * h;
;   { bf16* stg = (bf16*)(shm + LDS_OST) + wid * 2048;
; #pragma unroll
;     for (int r = 0; r < 16; ++r) { const int orow = crow(r, hi);
; #pragma unroll
;       for (int d0 = 0; d0 < 2; ++d0) stg[orow * 64 + d0 * 32 + r32] = (bf16)(cvtpk_s(o[d0][r] * rli[r], 0.f) & 0xffffu); }
;     asm volatile("s_waitcnt lgkmcnt(0)" ::: "memory");
; #pragma unroll
;     for (int i = 0; i < 4; ++i) { const int row = i * 8 + (lane >> 3), ch = lane & 7; const u32x4 v = *(const u32x4*)(stg + row * 64 + ch * 8); *(u32x4*)(Ow + (long)row * 1024 + ch * 8) = v; } }
;   asm volatile("s_waitcnt lgkmcnt(0)\n\ts_barrier" ::: "memory");
	v_mfma_f32_32x32x16_bf16 v[2:17], v[50:53], v[66:69], v[2:17]
	ds_read_b64_tr_b16 v[66:67], v157 offset:35840
	ds_read_b64_tr_b16 v[68:69], v157 offset:36352
	v_add_f32_e32 v34, v38, v34
	v_add_f32_e32 v34, v39, v34
	v_add_f32_e32 v34, v40, v34
	v_add_f32_e32 v34, v41, v34
	v_add_f32_e32 v34, v42, v34
	v_add_f32_e32 v34, v43, v34
	s_waitcnt lgkmcnt(0)
	v_mfma_f32_32x32x16_bf16 v[18:33], v[50:53], v[66:69], v[18:33]
	ds_read_b64_tr_b16 v[50:51], v157 offset:32768
	ds_read_b64_tr_b16 v[52:53], v157 offset:33280
	v_add_f32_e32 v34, v44, v34
	v_add_f32_e32 v34, v45, v34
	v_add_f32_e32 v34, v46, v34
	v_add_f32_e32 v34, v47, v34
	v_add_f32_e32 v34, v48, v34
	v_add_f32_e32 v34, v49, v34
	s_waitcnt lgkmcnt(0)
	v_mfma_f32_32x32x16_bf16 v[2:17], v[54:57], v[50:53], v[2:17]
	ds_read_b64_tr_b16 v[50:51], v157 offset:36864
	ds_read_b64_tr_b16 v[52:53], v157 offset:37376
	v_add_f32_e32 v0, v0, v34
	v_mov_b32_e32 v34, v0
	s_nop 1
	v_permlane32_swap_b32_e32 v0, v34
	s_waitcnt lgkmcnt(0)
	v_mfma_f32_32x32x16_bf16 v[18:33], v[54:57], v[50:53], v[18:33]
	ds_read_b64_tr_b16 v[52:53], v157 offset:39424
	ds_read_b64_tr_b16 v[54:55], v157 offset:33792
	ds_read_b64_tr_b16 v[56:57], v157 offset:34304
	ds_read_b64_tr_b16 v[66:67], v157 offset:37888
	ds_read_b64_tr_b16 v[68:69], v157 offset:38400
	ds_read_b64_tr_b16 v[70:71], v157 offset:34816
	ds_read_b64_tr_b16 v[72:73], v157 offset:35328
	ds_read_b64_tr_b16 v[50:51], v157 offset:38912
	s_waitcnt lgkmcnt(5)
	v_mfma_f32_32x32x16_bf16 v[2:17], v[58:61], v[54:57], v[2:17]
	s_waitcnt lgkmcnt(3)
	v_mfma_f32_32x32x16_bf16 v[18:33], v[58:61], v[66:69], v[18:33]
	s_waitcnt lgkmcnt(1)
	v_mfma_f32_32x32x16_bf16 v[2:17], v[62:65], v[70:73], v[2:17]
	s_waitcnt lgkmcnt(0)
	v_mfma_f32_32x32x16_bf16 v[18:33], v[62:65], v[50:53], v[18:33]
	s_and_saveexec_b64 s[6:7], s[4:5]
	v_lshl_add_u32 v35, v150, 2, s8
	v_add_f32_e32 v0, v0, v34
	ds_write_b32 v35, v0 offset:40064
	s_or_b64 exec, exec, s[6:7]
	s_waitcnt lgkmcnt(0)
	v_add_u32_e32 v0, s8, v158
	ds_read_b128 v[34:37], v0 offset:40064
	ds_read_b128 v[38:41], v0 offset:40096
	s_ashr_i32 s1, s0, 31
	s_lshl_b64 s[0:1], s[0:1], 11
	s_add_u32 s0, s18, s0
	s_waitcnt lgkmcnt(1)
	v_rcp_f32_e32 v42, v34
	v_rcp_f32_e32 v43, v35
	v_rcp_f32_e32 v44, v36
	v_rcp_f32_e32 v45, v37
	s_waitcnt lgkmcnt(0)
	v_rcp_f32_e32 v46, v38
	ds_read_b128 v[34:37], v0 offset:40128
	v_rcp_f32_e32 v47, v39
	v_rcp_f32_e32 v48, v40
	v_rcp_f32_e32 v49, v41
	ds_read_b128 v[38:41], v0 offset:40160
	s_addc_u32 s1, s19, s1
	s_lshl_b32 s6, s41, 12
	s_waitcnt lgkmcnt(1)
	v_rcp_f32_e32 v0, v34
	v_rcp_f32_e32 v34, v35
	v_rcp_f32_e32 v35, v36
	v_rcp_f32_e32 v36, v37
	s_waitcnt lgkmcnt(0)
	v_rcp_f32_e32 v37, v38
	v_rcp_f32_e32 v38, v39
	v_rcp_f32_e32 v39, v40
	v_rcp_f32_e32 v40, v41
	s_add_i32 s6, s6, 0
	v_mul_f32_e32 v2, v2, v42
	v_lshlrev_b32_e32 v41, 1, v156
	v_lshlrev_b32_e32 v50, 1, v150
	v_cvt_pk_bf16_f32 v2, v2, s0
	v_add3_u32 v41, s6, v41, v50
	ds_write_b16 v41, v2 offset:41984
	v_mul_f32_e32 v2, v18, v42
	v_cvt_pk_bf16_f32 v2, v2, s0
	ds_write_b16 v41, v2 offset:42048
	v_mul_f32_e32 v2, v3, v43
	v_cvt_pk_bf16_f32 v2, v2, s0
	ds_write_b16 v41, v2 offset:42112
	v_mul_f32_e32 v2, v19, v43
	v_cvt_pk_bf16_f32 v2, v2, s0
	ds_write_b16 v41, v2 offset:42176
	v_mul_f32_e32 v2, v4, v44
	v_cvt_pk_bf16_f32 v2, v2, s0
	ds_write_b16 v41, v2 offset:42240
	v_mul_f32_e32 v2, v20, v44
	v_cvt_pk_bf16_f32 v2, v2, s0
	ds_write_b16 v41, v2 offset:42304
	v_mul_f32_e32 v2, v5, v45
	v_cvt_pk_bf16_f32 v2, v2, s0
	ds_write_b16 v41, v2 offset:42368
	v_mul_f32_e32 v2, v21, v45
	v_cvt_pk_bf16_f32 v2, v2, s0
	ds_write_b16 v41, v2 offset:42432
	v_mul_f32_e32 v2, v6, v46
	v_cvt_pk_bf16_f32 v2, v2, s0
	ds_write_b16 v41, v2 offset:43008
	v_mul_f32_e32 v2, v22, v46
	v_cvt_pk_bf16_f32 v2, v2, s0
	ds_write_b16 v41, v2 offset:43072
	v_mul_f32_e32 v2, v7, v47
	v_cvt_pk_bf16_f32 v2, v2, s0
	ds_write_b16 v41, v2 offset:43136
	v_mul_f32_e32 v2, v23, v47
	v_cvt_pk_bf16_f32 v2, v2, s0
	ds_write_b16 v41, v2 offset:43200
	v_mul_f32_e32 v2, v8, v48
	v_cvt_pk_bf16_f32 v2, v2, s0
	ds_write_b16 v41, v2 offset:43264
	v_mul_f32_e32 v2, v24, v48
	v_cvt_pk_bf16_f32 v2, v2, s0
	ds_write_b16 v41, v2 offset:43328
	v_mul_f32_e32 v2, v9, v49
	v_cvt_pk_bf16_f32 v2, v2, s0
	ds_write_b16 v41, v2 offset:43392
	v_mul_f32_e32 v2, v25, v49
	v_cvt_pk_bf16_f32 v2, v2, s0
	ds_write_b16 v41, v2 offset:43456
	v_mul_f32_e32 v2, v10, v0
	v_mul_f32_e32 v0, v26, v0
	v_cvt_pk_bf16_f32 v0, v0, s0
	ds_write_b16 v41, v0 offset:44096
	v_mul_f32_e32 v0, v11, v34
	v_cvt_pk_bf16_f32 v0, v0, s0
	ds_write_b16 v41, v0 offset:44160
	v_mul_f32_e32 v0, v27, v34
	v_cvt_pk_bf16_f32 v0, v0, s0
	ds_write_b16 v41, v0 offset:44224
	v_mul_f32_e32 v0, v12, v35
	v_cvt_pk_bf16_f32 v0, v0, s0
	ds_write_b16 v41, v0 offset:44288
	v_mul_f32_e32 v0, v28, v35
	v_cvt_pk_bf16_f32 v0, v0, s0
	ds_write_b16 v41, v0 offset:44352
	v_mul_f32_e32 v0, v13, v36
	v_cvt_pk_bf16_f32 v0, v0, s0
	ds_write_b16 v41, v0 offset:44416
	v_mul_f32_e32 v0, v29, v36
	v_cvt_pk_bf16_f32 v0, v0, s0
	ds_write_b16 v41, v0 offset:44480
	v_mul_f32_e32 v0, v14, v37
	v_cvt_pk_bf16_f32 v0, v0, s0
	ds_write_b16 v41, v0 offset:45056
	v_mul_f32_e32 v0, v30, v37
	v_cvt_pk_bf16_f32 v0, v0, s0
	ds_write_b16 v41, v0 offset:45120
	v_mul_f32_e32 v0, v15, v38
	v_cvt_pk_bf16_f32 v0, v0, s0
	ds_write_b16 v41, v0 offset:45184
	v_mul_f32_e32 v0, v31, v38
	v_cvt_pk_bf16_f32 v0, v0, s0
	ds_write_b16 v41, v0 offset:45248
	v_mul_f32_e32 v0, v16, v39
	v_cvt_pk_bf16_f32 v0, v0, s0
	ds_write_b16 v41, v0 offset:45312
	v_mul_f32_e32 v0, v32, v39
	v_cvt_pk_bf16_f32 v0, v0, s0
	ds_write_b16 v41, v0 offset:45376
	v_mul_f32_e32 v0, v17, v40
	v_cvt_pk_bf16_f32 v0, v0, s0
	ds_write_b16 v41, v0 offset:45440
	v_mul_f32_e32 v0, v33, v40
	v_cvt_pk_bf16_f32 v2, v2, s0
	v_cvt_pk_bf16_f32 v0, v0, s0
	ds_write_b16 v41, v2 offset:44032
	ds_write_b16 v41, v0 offset:45504
	v_add_u32_e32 v0, s6, v138
	v_readlane_b32 s8, v243, 9
	s_waitcnt lgkmcnt(0)
	v_add_u32_e32 v2, v0, v159
	s_lshl_b32 s7, s8, 1
	ds_read_b128 v[2:5], v2 offset:41984
	v_add_u32_e32 v6, v0, v160
	s_add_u32 s0, s0, s7
	ds_read_b128 v[6:9], v6 offset:41984
	s_addc_u32 s1, s1, 0
	v_mov_b32_e32 v139, v1
	v_lshl_add_u64 v[10:11], s[0:1], 0, v[138:139]
	v_mov_b32_e32 v141, v1
	v_lshl_add_u64 v[12:13], v[10:11], 0, v[140:141]
	v_mov_b32_e32 v143, v1
	s_waitcnt lgkmcnt(1)
	global_store_dwordx4 v[12:13], v[2:5], off
	v_mov_b32_e32 v145, v1
	v_lshl_add_u64 v[12:13], v[10:11], 0, v[144:145]
	v_lshl_add_u64 v[2:3], v[10:11], 0, v[142:143]
	s_waitcnt lgkmcnt(0)
	global_store_dwordx4 v[2:3], v[6:9], off
	v_add_u32_e32 v2, v0, v161
	ds_read_b128 v[2:5], v2 offset:41984
	v_add_u32_e32 v0, v0, v162
	ds_read_b128 v[6:9], v0 offset:41984
	v_mov_b32_e32 v147, v1
	s_waitcnt lgkmcnt(1)
	global_store_dwordx4 v[12:13], v[2:5], off
	v_readlane_b32 s9, v243, 10
	s_nop 0
	v_lshl_add_u64 v[2:3], v[10:11], 0, v[146:147]
	s_waitcnt lgkmcnt(0)
	global_store_dwordx4 v[2:3], v[6:9], off
	s_waitcnt lgkmcnt(0)
	s_barrier
	s_branch .LBB0_60

; __device__ __forceinline__ unsigned xb_ld(unsigned* p)              { return __hip_atomic_load(p, __ATOMIC_RELAXED, __HIP_MEMORY_SCOPE_AGENT); }
; __device__ __forceinline__ unsigned xb_add(unsigned* p, unsigned v) { return __hip_atomic_fetch_add(p, v, __ATOMIC_RELAXED, __HIP_MEMORY_SCOPE_AGENT); }
; #define XB_SPIN(cond, bar) do { unsigned _sp = 0; while (cond) { __builtin_amdgcn_s_sleep(0);     \
;     if ((++_sp & 255u) == 0u) { if (xb_ld(&(bar)[XB_TMO])) break; if (_sp > XB_SPIN_CAP) { atomicAdd(&(bar)[XB_TMO], 1u); break; } } } } while (0)
; __device__ __forceinline__ void xcd_barrier(const XcdBarrier& b) {
;     ...
;         unsigned nloc = b.st[0], nx = b.st[1];
;         if (nloc == 0u) { xcd_barrier_complete(bar, b.x, nloc, nx); b.st[0] = nloc; b.st[1] = nx; }
;         const unsigned old = xb_add(&bar[XB_XSUB(b.x)], 1u);
;         const unsigned gen = old / nloc;
;         if (old + 1u == (gen + 1u) * nloc) {
;             __builtin_amdgcn_fence(__ATOMIC_RELEASE, "agent");
;             asm volatile("s_waitcnt vmcnt(0)" ::: "memory");
;             const unsigned og = xb_add(&bar[XB_TOP], 1u);
;             const unsigned tg = og / nx;
;             if (og + 1u == (tg + 1u) * nx) xb_add(&bar[XB_TOPGEN], 1u);
;             else XB_SPIN(xb_ld(&bar[XB_TOPGEN]) == tg, bar);
;             __builtin_amdgcn_fence(__ATOMIC_ACQUIRE, "agent");
;             xb_add(&bar[XB_XGEN(b.x)], 1u);
;             asm volatile("s_waitcnt vmcnt(0)" ::: "memory");
;         } else {
;             XB_SPIN(xb_ld(&bar[XB_XGEN(b.x)]) == gen, bar);
.LBB0_1248:
	s_or_b64 exec, exec, s[6:7]
	v_cvt_f32_u32_e32 v5, v3
	s_waitcnt vmcnt(0)
	v_readfirstlane_b32 s4, v4
	v_sub_u32_e32 v4, 0, v3
	v_rcp_iflag_f32_e32 v5, v5
	v_add_u32_e32 v6, s4, v0
	v_mul_f32_e32 v5, 0x4f7ffffe, v5
	v_cvt_u32_f32_e32 v5, v5
	v_mul_lo_u32 v0, v4, v5
	v_mul_hi_u32 v0, v5, v0
	v_add_u32_e32 v0, v5, v0
	v_mul_hi_u32 v0, v6, v0
	v_mul_lo_u32 v4, v0, v3
	v_sub_u32_e32 v4, v6, v4
	v_add_u32_e32 v5, 1, v0
	v_cmp_ge_u32_e32 vcc, v4, v3
	s_nop 1
	v_cndmask_b32_e32 v0, v0, v5, vcc
	v_sub_u32_e32 v5, v4, v3
	v_cndmask_b32_e32 v4, v4, v5, vcc
	v_add_u32_e32 v5, 1, v0
	v_cmp_ge_u32_e32 vcc, v4, v3
	v_add_u32_e32 v4, 1, v6
	s_nop 0
	v_cndmask_b32_e32 v0, v0, v5, vcc
	v_mul_lo_u32 v5, v3, v0
	v_add_u32_e32 v3, v5, v3
	v_cmp_ne_u32_e32 vcc, v4, v3
	s_and_saveexec_b64 s[4:5], vcc
	s_xor_b64 s[4:5], exec, s[4:5]
	s_cbranch_execz .LBB0_1262
	s_waitcnt lgkmcnt(0)
	buffer_inv sc1
	global_load_dword v2, v190, s[2:3] offset:1024 sc1
	s_add_u32 s10, s2, 0x2400
	s_addc_u32 s11, s3, 0
	s_waitcnt vmcnt(0)
	v_cmp_eq_u32_e32 vcc, v2, v0
	s_and_saveexec_b64 s[6:7], vcc
	s_cbranch_execz .LBB0_1261
	s_add_u32 s8, s80, 0x4200
	s_addc_u32 s9, s81, 0
	s_mov_b32 s22, 1
	s_mov_b64 s[12:13], 0
	s_branch .LBB0_1252

; __device__ __forceinline__ unsigned xb_ld(unsigned* p)              { return __hip_atomic_load(p, __ATOMIC_RELAXED, __HIP_MEMORY_SCOPE_AGENT); }
; #define XB_SPIN(cond, bar) do { unsigned _sp = 0; while (cond) { __builtin_amdgcn_s_sleep(0);     \
;     if ((++_sp & 255u) == 0u) { if (xb_ld(&(bar)[XB_TMO])) break; if (_sp > XB_SPIN_CAP) { atomicAdd(&(bar)[XB_TMO], 1u); break; } } } } while (0)
; __device__ __forceinline__ void xcd_barrier(const XcdBarrier& b) {
;     ...
;             XB_SPIN(xb_ld(&bar[XB_XGEN(b.x)]) == gen, bar);
;             __builtin_amdgcn_fence(__ATOMIC_ACQUIRE, "agent");
;             asm volatile("s_waitcnt vmcnt(0)" ::: "memory");
.LBB0_1261:
	s_or_b64 exec, exec, s[6:7]
	s_waitcnt vmcnt(0)
	s_waitcnt vmcnt(0)
